# gate/up phase start: gather-table build loads issued together (16 per thread) instead of one load->wait->LDS write per iteration
# speedup vs baseline: 1.0069x; 1.0069x over previous
; #define LAS __attribute__((address_space(3)))
;     __device__ bool next(int i, Unit& u) const {
;     ...
;         if ((G & 7) == 0 && (G >> 3) % nN == 0) { const int xcd = c & 7, j = c >> 3, per = (G >> 3) / nN; pn = j % nN; mt = (i * per + j / nN) * 8 + xcd; }
;         else { const int L = i * G + c; mt = L / nN; pn = L % nN; }
;         if (mt >= MT) return false;
;         u.pm = mt; u.pn = pn; int e = 0;
;         for (int j = 1; j < NEXP; ++j) e += (mpre[j] <= mt) ? 1 : 0;
;         u.e = __builtin_amdgcn_readfirstlane(e); return true;
; __device__ __forceinline__ void run_phase(const Args& a, const int ph, LAS unsigned char* lds, const int tid, const int rpt) {
;     ...
;                 { LAS unsigned short* RT = (LAS unsigned short*)(lds + TAB_OFF + 256); const int* rowslot = (const int*)(ws + WS_ROWSLOT);
;                   for (int idx = tid; idx < 31 * 256; idx += 512) { pg8::Unit u; if (S.next(idx >> 8, u)) RT[idx] = (unsigned short)(rowslot[u.pm * 256 + (idx & 255)] >> 2); }
;                   __syncthreads(); S.rt = RT; }
.LBB0_72:
	s_or_b64 exec, exec, s[0:1]
	v_readlane_b32 s0, v253, 63
	s_waitcnt lgkmcnt(0)
	s_barrier
	v_mov_b32_e32 v0, s0
	ds_read_b32 v0, v0
	s_movk_i32 s0, 0x1f00
	v_cmp_gt_i32_e32 vcc, s0, v168
	v_readlane_b32 s0, v249, 49
	s_and_b32 s12, s0, 63
	s_waitcnt lgkmcnt(0)
	v_readfirstlane_b32 s15, v0
	s_and_saveexec_b64 s[0:1], vcc
	s_cbranch_execz .LBB0_81
	s_cmp_lg_u32 s12, 0
	v_readlane_b32 s20, v249, 49
	s_cselect_b64 s[16:17], -1, 0
	s_ashr_i32 s26, s20, 6
	v_readlane_b32 s20, v254, 16
	v_and_b32_e32 v0, 0xff, v168
	v_mov_b32_e32 v2, v168
	v_lshl_add_u32 v1, v168, 1, s20
	s_mov_b64 s[20:21], 0
	s_cmp_eq_u32 s12, 0
	s_cbranch_scc0 .LBB0_75
	v_readlane_b32 s22, v251, 35
	v_readlane_b32 s23, v251, 37
	v_readlane_b32 s36, v251, 25
	v_readlane_b32 s37, v251, 26
	s_add_i32 s98, s15, 7
	s_lshr_b32 s98, s98, 3
	s_mul_i32 s99, s23, s98
	v_lshrrev_b32_e32 v6, 8, v168
	v_add_u32_e32 v3, 0, v6
	v_mul_lo_u32 v3, v3, s26
	v_add_u32_e32 v3, s22, v3
	v_add_u32_e32 v4, s99, v3
	v_cmp_gt_u32_e32 vcc, s98, v3
	v_cmp_gt_i32_e64 s[100:101], s15, v4
	s_and_b64 vcc, vcc, s[100:101]
	v_mov_b32_e32 v8, -1
	v_lshl_or_b32 v4, v4, 8, v0
	v_mov_b32_e32 v5, 0
	v_lshl_add_u64 v[4:5], v[4:5], 2, s[36:37]
	s_and_saveexec_b64 s[100:101], vcc
	global_load_dword v8, v[4:5], off
	s_mov_b64 exec, s[100:101]
	v_add_u32_e32 v3, 2, v6
	v_mul_lo_u32 v3, v3, s26
	v_add_u32_e32 v3, s22, v3
	v_add_u32_e32 v4, s99, v3
	v_cmp_gt_u32_e32 vcc, s98, v3
	v_cmp_gt_i32_e64 s[100:101], s15, v4
	s_and_b64 vcc, vcc, s[100:101]
	v_mov_b32_e32 v9, -1
	v_lshl_or_b32 v4, v4, 8, v0
	v_mov_b32_e32 v5, 0
	v_lshl_add_u64 v[4:5], v[4:5], 2, s[36:37]
	s_and_saveexec_b64 s[100:101], vcc
	global_load_dword v9, v[4:5], off
	s_mov_b64 exec, s[100:101]
	v_add_u32_e32 v3, 4, v6
	v_mul_lo_u32 v3, v3, s26
	v_add_u32_e32 v3, s22, v3
	v_add_u32_e32 v4, s99, v3
	v_cmp_gt_u32_e32 vcc, s98, v3
	v_cmp_gt_i32_e64 s[100:101], s15, v4
	s_and_b64 vcc, vcc, s[100:101]
	v_mov_b32_e32 v10, -1
	v_lshl_or_b32 v4, v4, 8, v0
	v_mov_b32_e32 v5, 0
	v_lshl_add_u64 v[4:5], v[4:5], 2, s[36:37]
	s_and_saveexec_b64 s[100:101], vcc
	global_load_dword v10, v[4:5], off
	s_mov_b64 exec, s[100:101]
	v_add_u32_e32 v3, 6, v6
	v_mul_lo_u32 v3, v3, s26
	v_add_u32_e32 v3, s22, v3
	v_add_u32_e32 v4, s99, v3
	v_cmp_gt_u32_e32 vcc, s98, v3
	v_cmp_gt_i32_e64 s[100:101], s15, v4
	s_and_b64 vcc, vcc, s[100:101]
	v_mov_b32_e32 v11, -1
	v_lshl_or_b32 v4, v4, 8, v0
	v_mov_b32_e32 v5, 0
	v_lshl_add_u64 v[4:5], v[4:5], 2, s[36:37]
	s_and_saveexec_b64 s[100:101], vcc
	global_load_dword v11, v[4:5], off
	s_mov_b64 exec, s[100:101]
	v_add_u32_e32 v3, 8, v6
	v_mul_lo_u32 v3, v3, s26
	v_add_u32_e32 v3, s22, v3
	v_add_u32_e32 v4, s99, v3
	v_cmp_gt_u32_e32 vcc, s98, v3
	v_cmp_gt_i32_e64 s[100:101], s15, v4
	s_and_b64 vcc, vcc, s[100:101]
	v_mov_b32_e32 v12, -1
	v_lshl_or_b32 v4, v4, 8, v0
	v_mov_b32_e32 v5, 0
	v_lshl_add_u64 v[4:5], v[4:5], 2, s[36:37]
	s_and_saveexec_b64 s[100:101], vcc
	global_load_dword v12, v[4:5], off
	s_mov_b64 exec, s[100:101]
	v_add_u32_e32 v3, 10, v6
	v_mul_lo_u32 v3, v3, s26
	v_add_u32_e32 v3, s22, v3
	v_add_u32_e32 v4, s99, v3
	v_cmp_gt_u32_e32 vcc, s98, v3
	v_cmp_gt_i32_e64 s[100:101], s15, v4
	s_and_b64 vcc, vcc, s[100:101]
	v_mov_b32_e32 v13, -1
	v_lshl_or_b32 v4, v4, 8, v0
	v_mov_b32_e32 v5, 0
	v_lshl_add_u64 v[4:5], v[4:5], 2, s[36:37]
	s_and_saveexec_b64 s[100:101], vcc
	global_load_dword v13, v[4:5], off
	s_mov_b64 exec, s[100:101]
	v_add_u32_e32 v3, 12, v6
	v_mul_lo_u32 v3, v3, s26
	v_add_u32_e32 v3, s22, v3
	v_add_u32_e32 v4, s99, v3
	v_cmp_gt_u32_e32 vcc, s98, v3
	v_cmp_gt_i32_e64 s[100:101], s15, v4
	s_and_b64 vcc, vcc, s[100:101]
	v_mov_b32_e32 v14, -1
	v_lshl_or_b32 v4, v4, 8, v0
	v_mov_b32_e32 v5, 0
	v_lshl_add_u64 v[4:5], v[4:5], 2, s[36:37]
	s_and_saveexec_b64 s[100:101], vcc
	global_load_dword v14, v[4:5], off
	s_mov_b64 exec, s[100:101]
	v_add_u32_e32 v3, 14, v6
	v_mul_lo_u32 v3, v3, s26
	v_add_u32_e32 v3, s22, v3
	v_add_u32_e32 v4, s99, v3
	v_cmp_gt_u32_e32 vcc, s98, v3
	v_cmp_gt_i32_e64 s[100:101], s15, v4
	s_and_b64 vcc, vcc, s[100:101]
	v_mov_b32_e32 v15, -1
	v_lshl_or_b32 v4, v4, 8, v0
	v_mov_b32_e32 v5, 0
	v_lshl_add_u64 v[4:5], v[4:5], 2, s[36:37]
	s_and_saveexec_b64 s[100:101], vcc
	global_load_dword v15, v[4:5], off
	s_mov_b64 exec, s[100:101]
	v_add_u32_e32 v3, 16, v6
	v_mul_lo_u32 v3, v3, s26
	v_add_u32_e32 v3, s22, v3
	v_add_u32_e32 v4, s99, v3
	v_cmp_gt_u32_e32 vcc, s98, v3
	v_cmp_gt_i32_e64 s[100:101], s15, v4
	s_and_b64 vcc, vcc, s[100:101]
	v_mov_b32_e32 v16, -1
	v_lshl_or_b32 v4, v4, 8, v0
	v_mov_b32_e32 v5, 0
	v_lshl_add_u64 v[4:5], v[4:5], 2, s[36:37]
	s_and_saveexec_b64 s[100:101], vcc
	global_load_dword v16, v[4:5], off
	s_mov_b64 exec, s[100:101]
	v_add_u32_e32 v3, 18, v6
	v_mul_lo_u32 v3, v3, s26
	v_add_u32_e32 v3, s22, v3
	v_add_u32_e32 v4, s99, v3
	v_cmp_gt_u32_e32 vcc, s98, v3
	v_cmp_gt_i32_e64 s[100:101], s15, v4
	s_and_b64 vcc, vcc, s[100:101]
	v_mov_b32_e32 v17, -1
	v_lshl_or_b32 v4, v4, 8, v0
	v_mov_b32_e32 v5, 0
	v_lshl_add_u64 v[4:5], v[4:5], 2, s[36:37]
	s_and_saveexec_b64 s[100:101], vcc
	global_load_dword v17, v[4:5], off
	s_mov_b64 exec, s[100:101]
	v_add_u32_e32 v3, 20, v6
	v_mul_lo_u32 v3, v3, s26
	v_add_u32_e32 v3, s22, v3
; #define LAS __attribute__((address_space(3)))
; __device__ __forceinline__ void run_phase(const Args& a, const int ph, LAS unsigned char* lds, const int tid, const int rpt) {
;     ...
;                 { LAS unsigned short* RT = (LAS unsigned short*)(lds + TAB_OFF + 256); const int* rowslot = (const int*)(ws + WS_ROWSLOT);
;                   for (int idx = tid; idx < 31 * 256; idx += 512) { pg8::Unit u; if (S.next(idx >> 8, u)) RT[idx] = (unsigned short)(rowslot[u.pm * 256 + (idx & 255)] >> 2); }
;                   __syncthreads(); S.rt = RT; }
	v_add_u32_e32 v4, s99, v3
	v_cmp_gt_u32_e32 vcc, s98, v3
	v_cmp_gt_i32_e64 s[100:101], s15, v4
	s_and_b64 vcc, vcc, s[100:101]
	v_mov_b32_e32 v18, -1
	v_lshl_or_b32 v4, v4, 8, v0
	v_mov_b32_e32 v5, 0
	v_lshl_add_u64 v[4:5], v[4:5], 2, s[36:37]
	s_and_saveexec_b64 s[100:101], vcc
	global_load_dword v18, v[4:5], off
	s_mov_b64 exec, s[100:101]
	v_add_u32_e32 v3, 22, v6
	v_mul_lo_u32 v3, v3, s26
	v_add_u32_e32 v3, s22, v3
	v_add_u32_e32 v4, s99, v3
	v_cmp_gt_u32_e32 vcc, s98, v3
	v_cmp_gt_i32_e64 s[100:101], s15, v4
	s_and_b64 vcc, vcc, s[100:101]
	v_mov_b32_e32 v19, -1
	v_lshl_or_b32 v4, v4, 8, v0
	v_mov_b32_e32 v5, 0
	v_lshl_add_u64 v[4:5], v[4:5], 2, s[36:37]
	s_and_saveexec_b64 s[100:101], vcc
	global_load_dword v19, v[4:5], off
	s_mov_b64 exec, s[100:101]
	v_add_u32_e32 v3, 24, v6
	v_mul_lo_u32 v3, v3, s26
	v_add_u32_e32 v3, s22, v3
	v_add_u32_e32 v4, s99, v3
	v_cmp_gt_u32_e32 vcc, s98, v3
	v_cmp_gt_i32_e64 s[100:101], s15, v4
	s_and_b64 vcc, vcc, s[100:101]
	v_mov_b32_e32 v20, -1
	v_lshl_or_b32 v4, v4, 8, v0
	v_mov_b32_e32 v5, 0
	v_lshl_add_u64 v[4:5], v[4:5], 2, s[36:37]
	s_and_saveexec_b64 s[100:101], vcc
	global_load_dword v20, v[4:5], off
	s_mov_b64 exec, s[100:101]
	v_add_u32_e32 v3, 26, v6
	v_mul_lo_u32 v3, v3, s26
	v_add_u32_e32 v3, s22, v3
	v_add_u32_e32 v4, s99, v3
	v_cmp_gt_u32_e32 vcc, s98, v3
	v_cmp_gt_i32_e64 s[100:101], s15, v4
	s_and_b64 vcc, vcc, s[100:101]
	v_mov_b32_e32 v21, -1
	v_lshl_or_b32 v4, v4, 8, v0
	v_mov_b32_e32 v5, 0
	v_lshl_add_u64 v[4:5], v[4:5], 2, s[36:37]
	s_and_saveexec_b64 s[100:101], vcc
	global_load_dword v21, v[4:5], off
	s_mov_b64 exec, s[100:101]
	v_add_u32_e32 v3, 28, v6
	v_mul_lo_u32 v3, v3, s26
	v_add_u32_e32 v3, s22, v3
	v_add_u32_e32 v4, s99, v3
	v_cmp_gt_u32_e32 vcc, s98, v3
	v_cmp_gt_i32_e64 s[100:101], s15, v4
	s_and_b64 vcc, vcc, s[100:101]
	v_mov_b32_e32 v22, -1
	v_lshl_or_b32 v4, v4, 8, v0
	v_mov_b32_e32 v5, 0
	v_lshl_add_u64 v[4:5], v[4:5], 2, s[36:37]
	s_and_saveexec_b64 s[100:101], vcc
	global_load_dword v22, v[4:5], off
	s_mov_b64 exec, s[100:101]
	v_add_u32_e32 v3, 30, v6
	v_mul_lo_u32 v3, v3, s26
	v_add_u32_e32 v3, s22, v3
	v_add_u32_e32 v4, s99, v3
	v_cmp_gt_u32_e32 vcc, s98, v3
	v_cmp_gt_i32_e64 s[100:101], s15, v4
	s_and_b64 vcc, vcc, s[100:101]
	s_movk_i32 s20, 0x100
	v_cmp_gt_u32_e64 s[100:101], s20, v168
	s_and_b64 vcc, vcc, s[100:101]
	v_mov_b32_e32 v23, -1
	v_lshl_or_b32 v4, v4, 8, v0
	v_mov_b32_e32 v5, 0
	v_lshl_add_u64 v[4:5], v[4:5], 2, s[36:37]
	s_and_saveexec_b64 s[100:101], vcc
	global_load_dword v23, v[4:5], off
	s_mov_b64 exec, s[100:101]
	s_waitcnt vmcnt(0)
	v_cmp_ne_u32_e32 vcc, -1, v8
	s_and_saveexec_b64 s[100:101], vcc
	v_lshrrev_b32_e32 v8, 2, v8
	ds_write_b16 v1, v8
	s_mov_b64 exec, s[100:101]
	v_cmp_ne_u32_e32 vcc, -1, v9
	s_and_saveexec_b64 s[100:101], vcc
	v_lshrrev_b32_e32 v9, 2, v9
	ds_write_b16 v1, v9 offset:1024
	s_mov_b64 exec, s[100:101]
	v_cmp_ne_u32_e32 vcc, -1, v10
	s_and_saveexec_b64 s[100:101], vcc
	v_lshrrev_b32_e32 v10, 2, v10
	ds_write_b16 v1, v10 offset:2048
	s_mov_b64 exec, s[100:101]
	v_cmp_ne_u32_e32 vcc, -1, v11
	s_and_saveexec_b64 s[100:101], vcc
	v_lshrrev_b32_e32 v11, 2, v11
	ds_write_b16 v1, v11 offset:3072
	s_mov_b64 exec, s[100:101]
	v_cmp_ne_u32_e32 vcc, -1, v12
	s_and_saveexec_b64 s[100:101], vcc
	v_lshrrev_b32_e32 v12, 2, v12
	ds_write_b16 v1, v12 offset:4096
	s_mov_b64 exec, s[100:101]
	v_cmp_ne_u32_e32 vcc, -1, v13
	s_and_saveexec_b64 s[100:101], vcc
	v_lshrrev_b32_e32 v13, 2, v13
	ds_write_b16 v1, v13 offset:5120
	s_mov_b64 exec, s[100:101]
	v_cmp_ne_u32_e32 vcc, -1, v14
	s_and_saveexec_b64 s[100:101], vcc
	v_lshrrev_b32_e32 v14, 2, v14
	ds_write_b16 v1, v14 offset:6144
	s_mov_b64 exec, s[100:101]
	v_cmp_ne_u32_e32 vcc, -1, v15
	s_and_saveexec_b64 s[100:101], vcc
	v_lshrrev_b32_e32 v15, 2, v15
	ds_write_b16 v1, v15 offset:7168
	s_mov_b64 exec, s[100:101]
	v_cmp_ne_u32_e32 vcc, -1, v16
	s_and_saveexec_b64 s[100:101], vcc
	v_lshrrev_b32_e32 v16, 2, v16
	ds_write_b16 v1, v16 offset:8192
	s_mov_b64 exec, s[100:101]
	v_cmp_ne_u32_e32 vcc, -1, v17
	s_and_saveexec_b64 s[100:101], vcc
	v_lshrrev_b32_e32 v17, 2, v17
	ds_write_b16 v1, v17 offset:9216
	s_mov_b64 exec, s[100:101]
	v_cmp_ne_u32_e32 vcc, -1, v18
	s_and_saveexec_b64 s[100:101], vcc
	v_lshrrev_b32_e32 v18, 2, v18
	ds_write_b16 v1, v18 offset:10240
	s_mov_b64 exec, s[100:101]
	v_cmp_ne_u32_e32 vcc, -1, v19
	s_and_saveexec_b64 s[100:101], vcc
	v_lshrrev_b32_e32 v19, 2, v19
	ds_write_b16 v1, v19 offset:11264
	s_mov_b64 exec, s[100:101]
	v_cmp_ne_u32_e32 vcc, -1, v20
	s_and_saveexec_b64 s[100:101], vcc
	v_lshrrev_b32_e32 v20, 2, v20
	ds_write_b16 v1, v20 offset:12288
	s_mov_b64 exec, s[100:101]
	v_cmp_ne_u32_e32 vcc, -1, v21
	s_and_saveexec_b64 s[100:101], vcc
	v_lshrrev_b32_e32 v21, 2, v21
	ds_write_b16 v1, v21 offset:13312
	s_mov_b64 exec, s[100:101]
	v_cmp_ne_u32_e32 vcc, -1, v22
	s_and_saveexec_b64 s[100:101], vcc
	v_lshrrev_b32_e32 v22, 2, v22
	ds_write_b16 v1, v22 offset:14336
	s_mov_b64 exec, s[100:101]
	v_cmp_ne_u32_e32 vcc, -1, v23
	s_and_saveexec_b64 s[100:101], vcc
	v_lshrrev_b32_e32 v23, 2, v23
	ds_write_b16 v1, v23 offset:15360
	s_mov_b64 exec, s[100:101]
	s_branch .LBB0_81
	s_branch .LBB0_75
